# lever 8 again: next pair's K loads and address math interleaved into the QK fp8 MFMA shadow of the selection loop
# speedup vs baseline: 1.0086x; 1.0051x over previous
; __device__ __forceinline__ void nsa_unit(const Params& p, int bg, int jq, LAS unsigned char* lds, int wave, int lane, bool build_lut) {
;     ...
;                 bool ok[2];
;                 ok[0] = (selw[(grp * 4 + q4) * 8 + (nb[0] >> 5)] >> (nb[0] & 31)) & 1u;
;                 ok[1] = real1 && ((selw[(grp * 4 + q4) * 8 + (nb[1] >> 5)] >> (nb[1] & 31)) & 1u);
;                 const int bmax = real1 ? max(nb[0], nb[1]) : nb[0];
;                 const bool fast = (tq0g - 64 * bmax - 63) >= 128;
;                 const bool fresh = m < -1e29f;
;                 const float mref = fresh ? 0.f : m;
;                 float ini[2];
;                 ini[0] = fast ? (ok[0] ? -(mref - lutfar16 - 6.0f) : NEG_INF) : 0.f;
;                 ini[1] = fast ? (ok[1] ? -(mref - lutfar16 - 6.0f) : NEG_INF) : 0.f;
;                 f32x4 sc[2][4];
; #pragma unroll
;                 for (int u = 0; u < 2; ++u)
; #pragma unroll
;                     for (int kt = 0; kt < 4; ++kt) {
;                         sc[u][kt] = __builtin_amdgcn_mfma_f32_16x16x32_fp8_fp8(k8[u][2 * kt], q8[0], (f32x4){ini[u], ini[u], ini[u], ini[u]}, 0, 0, 0);
;                         sc[u][kt] = __builtin_amdgcn_mfma_f32_16x16x32_fp8_fp8(k8[u][2 * kt + 1], q8[1], sc[u][kt], 0, 0, 0);
;                     }
;                 if (it + 1 < npair) {
;                     n0 = __builtin_amdgcn_readfirstlane(list[lbase + 2 * it + 2]); n1 = __builtin_amdgcn_readfirstlane(list[lbase + 2 * it + 3]);
; #pragma unroll
;                     for (int i = 0; i < 4; ++i) { const l64x2 t0 = *(const l64x2*)(ks8 + (size_t)n0 * 4096 + i * 1024 + lane * 16), t1 = *(const l64x2*)(ks8 + (size_t)n1 * 4096 + i * 1024 + lane * 16);
;                         k8[0][2 * i] = t0[0]; k8[0][2 * i + 1] = t0[1]; k8[1][2 * i] = t1[0]; k8[1][2 * i + 1] = t1[1]; }
;                 }
.LBB0_1202:
	s_max_i32 s6, s22, s8
	s_and_b64 s[4:5], s[4:5], exec
	s_cselect_b32 s4, s6, s22
	s_lshl_b32 s4, s4, 6
	s_sub_i32 s4, s39, s4
	s_cmpk_lt_i32 s4, 0xbf
	s_cselect_b64 s[24:25], -1, 0
	s_cmpk_gt_i32 s4, 0xbe
	v_cmp_ngt_f32_e64 s[4:5], s93, v157
	s_waitcnt lgkmcnt(0)
	v_lshrrev_b32_e32 v1, s22, v1
	v_and_b32_e32 v1, 1, v1
	v_cndmask_b32_e64 v156, 0, v157, s[4:5]
	v_sub_f32_e32 v2, v156, v161
	v_add_f32_e32 v2, 0xc0c00000, v2
	v_cmp_eq_u32_e64 s[6:7], 1, v1
	s_cselect_b64 vcc, -1, 0
	s_add_i32 s44, s44, 1
	v_cndmask_b32_e64 v1, v230, -v2, s[6:7]
	v_cndmask_b32_e32 v88, 0, v1, vcc
	v_mov_b32_e32 v89, v88
	v_mov_b32_e32 v90, v88
	v_mov_b32_e32 v91, v88
	v_cndmask_b32_e64 v1, v230, -v2, s[20:21]
	v_cndmask_b32_e32 v120, 0, v1, vcc
	s_cmp_ge_u32 s44, s41
	s_mov_b32 s16, s22
	s_mov_b32 s18, s8
	s_cbranch_scc1 .Lqk_last
	v_readfirstlane_b32 s16, v238
	v_readfirstlane_b32 s18, v239
	s_ashr_i32 s17, s16, 31
	s_lshl_b64 s[46:47], s[16:17], 12
	s_ashr_i32 s19, s18, 31
	v_lshl_add_u64 v[2:3], v[148:149], 0, s[46:47]
	s_lshl_b64 s[46:47], s[18:19], 12
	v_lshl_add_u64 v[238:239], v[148:149], 0, s[46:47]
	s_waitcnt vmcnt(8)
	v_mfma_f32_16x16x32_fp8_fp8 v[92:95], v[16:17], v[152:153], v[88:91]
	v_mov_b32_e32 v121, v120
	v_mov_b32_e32 v122, v120
	v_mov_b32_e32 v123, v120
	v_mfma_f32_16x16x32_fp8_fp8 v[116:119], v[18:19], v[154:155], v[92:95]
	global_load_dwordx4 v[16:19], v[2:3], off
	v_mfma_f32_16x16x32_fp8_fp8 v[92:95], v[28:29], v[152:153], v[88:91]
	v_mfma_f32_16x16x32_fp8_fp8 v[108:111], v[30:31], v[154:155], v[92:95]
	global_load_dwordx4 v[28:31], v[2:3], off offset:1024
	v_mfma_f32_16x16x32_fp8_fp8 v[92:95], v[20:21], v[152:153], v[88:91]
	v_mfma_f32_16x16x32_fp8_fp8 v[88:91], v[36:37], v[152:153], v[88:91]
	v_mfma_f32_16x16x32_fp8_fp8 v[100:103], v[38:39], v[154:155], v[88:91]
	global_load_dwordx4 v[36:39], v[2:3], off offset:3072
	v_mfma_f32_16x16x32_fp8_fp8 v[88:91], v[4:5], v[152:153], v[120:123]
	v_mfma_f32_16x16x32_fp8_fp8 v[112:115], v[6:7], v[154:155], v[88:91]
	global_load_dwordx4 v[4:7], v[238:239], off
	v_mfma_f32_16x16x32_fp8_fp8 v[88:91], v[12:13], v[152:153], v[120:123]
	v_mfma_f32_16x16x32_fp8_fp8 v[104:107], v[14:15], v[154:155], v[88:91]
	global_load_dwordx4 v[12:15], v[238:239], off offset:1024
	v_mfma_f32_16x16x32_fp8_fp8 v[88:91], v[8:9], v[152:153], v[120:123]
	v_mfma_f32_16x16x32_fp8_fp8 v[96:99], v[22:23], v[154:155], v[92:95]
	global_load_dwordx4 v[20:23], v[2:3], off offset:2048
	v_mfma_f32_16x16x32_fp8_fp8 v[92:95], v[10:11], v[154:155], v[88:91]
	global_load_dwordx4 v[8:11], v[238:239], off offset:2048
	v_mfma_f32_16x16x32_fp8_fp8 v[88:91], v[32:33], v[152:153], v[120:123]
	v_mfma_f32_16x16x32_fp8_fp8 v[88:91], v[34:35], v[154:155], v[88:91]
	global_load_dwordx4 v[32:35], v[238:239], off offset:3072
	s_branch .LBB0_1204
.Lqk_last:
	s_waitcnt vmcnt(8)
	v_mfma_f32_16x16x32_fp8_fp8 v[92:95], v[16:17], v[152:153], v[88:91]
	v_mov_b32_e32 v121, v120
	v_mov_b32_e32 v122, v120
	v_mov_b32_e32 v123, v120
	v_mfma_f32_16x16x32_fp8_fp8 v[116:119], v[18:19], v[154:155], v[92:95]
	v_mfma_f32_16x16x32_fp8_fp8 v[92:95], v[28:29], v[152:153], v[88:91]
	v_mfma_f32_16x16x32_fp8_fp8 v[108:111], v[30:31], v[154:155], v[92:95]
	v_mfma_f32_16x16x32_fp8_fp8 v[92:95], v[20:21], v[152:153], v[88:91]
	v_mfma_f32_16x16x32_fp8_fp8 v[88:91], v[36:37], v[152:153], v[88:91]
	v_mfma_f32_16x16x32_fp8_fp8 v[100:103], v[38:39], v[154:155], v[88:91]
	v_mfma_f32_16x16x32_fp8_fp8 v[88:91], v[4:5], v[152:153], v[120:123]
	v_mfma_f32_16x16x32_fp8_fp8 v[112:115], v[6:7], v[154:155], v[88:91]
	v_mfma_f32_16x16x32_fp8_fp8 v[88:91], v[12:13], v[152:153], v[120:123]
	v_mfma_f32_16x16x32_fp8_fp8 v[104:107], v[14:15], v[154:155], v[88:91]
	v_mfma_f32_16x16x32_fp8_fp8 v[88:91], v[8:9], v[152:153], v[120:123]
	v_mfma_f32_16x16x32_fp8_fp8 v[96:99], v[22:23], v[154:155], v[92:95]
	v_mfma_f32_16x16x32_fp8_fp8 v[92:95], v[10:11], v[154:155], v[88:91]
	v_mfma_f32_16x16x32_fp8_fp8 v[88:91], v[32:33], v[152:153], v[120:123]
	v_mfma_f32_16x16x32_fp8_fp8 v[88:91], v[34:35], v[154:155], v[88:91]
